# S5 passes: tasks renumbered so a workgroup keeps one (batch, group) for all its chunks (parameters L1-resident)
# baseline (speedup 1.0000x reference)
.LBB0_259:
	s_cmpk_eq_i32 s94, 0x800
	s_cbranch_scc1 .Ls5map_nf
	v_mul_hi_i32 v4, v67, s18
	v_lshrrev_b32_e32 v5, 31, v4
	v_ashrrev_i32_e32 v4, 5, v4
	v_add_u32_e32 v14, v4, v5
	v_mul_lo_u32 v4, v14, s19
	v_sub_u32_e32 v32, v67, v4
	s_branch .Ls5map_nf_done
.Ls5map_nf:
	v_and_b32_e32 v4, 0x7ff, v67
	v_lshrrev_b32_e32 v5, 11, v67
	v_lshrrev_b32_e32 v33, 2, v4
	v_and_b32_e32 v34, 3, v4
	v_cmp_eq_u32_e32 vcc, 16, v5
	v_add_u32_e32 v34, 0x80, v34
	v_and_b32_e32 v32, 7, v4
	v_lshl_add_u32 v32, v5, 3, v32
	v_lshrrev_b32_e32 v14, 3, v4
	v_cndmask_b32_e32 v32, v32, v34, vcc
	v_cndmask_b32_e32 v14, v14, v33, vcc
.Ls5map_nf_done:
	v_ashrrev_i32_e32 v62, 6, v14
	v_mov_b32_e32 v33, v189
	v_mov_b32_e32 v34, v189
	s_mov_b32 s0, s33
	v_cmp_lt_i32_e64 s[2:3], s20, v32
	v_cmp_gt_i32_e32 vcc, s21, v32
	v_lshlrev_b32_e32 v4, 6, v32
	v_ashrrev_i32_e32 v63, 31, v62
	s_and_saveexec_b64 s[0:1], vcc
	s_xor_b64 s[0:1], exec, s[0:1]
	v_lshlrev_b64 v[6:7], 13, v[62:63]
	v_ashrrev_i32_e32 v5, 31, v4
	v_lshl_add_u64 v[12:13], v[6:7], 0, v[4:5]
	s_andn2_saveexec_b64 s[0:1], s[0:1]
	v_lshlrev_b32_e32 v5, 8, v62
	v_add3_u32 v12, v4, v5, s22
	v_ashrrev_i32_e32 v13, 31, v12
	s_or_b64 exec, exec, s[0:1]
	global_load_dwordx2 v[28:29], v61, s[14:15] offset:32
	global_load_dwordx4 v[4:7], v61, s[14:15] offset:16
	global_load_dwordx4 v[8:11], v61, s[14:15]
	v_and_b32_e32 v66, 63, v14
	v_and_b32_e32 v64, 15, v34
	v_mov_b32_e32 v65, v61
	v_lshlrev_b32_e32 v60, 5, v66
	v_lshl_add_u64 v[12:13], v[12:13], 0, v[64:65]
	v_lshl_add_u64 v[14:15], s[60:61], 0, v[60:61]
	v_and_b32_e32 v60, 48, v34
	v_and_b32_e32 v75, 63, v34
	v_lshl_add_u64 v[14:15], v[14:15], 0, v[60:61]
	v_lshlrev_b64 v[12:13], 13, v[12:13]
	v_cmp_lt_u32_e64 s[0:1], 31, v75
	v_cmp_gt_u32_e64 s[6:7], 32, v75
	v_mov_b32_e32 v16, 0
	v_lshl_add_u64 v[30:31], v[14:15], 0, v[12:13]
	v_mov_b32_e32 v12, 0
	v_mov_b32_e32 v13, 0
	v_mov_b32_e32 v14, 0
	v_mov_b32_e32 v15, 0
	s_and_saveexec_b64 s[10:11], s[6:7]
	s_cbranch_execz .LBB0_265
	global_load_dwordx4 v[12:15], v[30:31], off

.LBB0_782:
	s_cmpk_eq_i32 s94, 0x800
	s_cbranch_scc1 .Ls5map_fi
	v_mul_hi_i32 v0, v125, s22
	v_lshrrev_b32_e32 v2, 31, v0
	v_ashrrev_i32_e32 v0, 5, v0
	v_add_u32_e32 v0, v0, v2
	v_mul_lo_u32 v2, v0, s23
	v_sub_u32_e32 v50, v125, v2
	s_branch .Ls5map_fi_done
.Ls5map_fi:
	v_and_b32_e32 v2, 0x7ff, v125
	v_lshrrev_b32_e32 v36, 11, v125
	v_lshrrev_b32_e32 v34, 2, v2
	v_and_b32_e32 v133, 3, v2
	v_cmp_eq_u32_e32 vcc, 16, v36
	v_add_u32_e32 v133, 0x80, v133
	v_and_b32_e32 v50, 7, v2
	v_lshl_add_u32 v50, v36, 3, v50
	v_lshrrev_b32_e32 v0, 3, v2
	v_cndmask_b32_e32 v50, v50, v133, vcc
	v_cndmask_b32_e32 v0, v0, v34, vcc
.Ls5map_fi_done:
	v_ashrrev_i32_e32 v132, 6, v0
	v_mov_b32_e32 v36, v189
	v_mov_b32_e32 v34, v189
	s_mov_b32 s0, s33
	v_cmp_lt_i32_e64 s[6:7], s24, v50
	v_cmp_gt_i32_e32 vcc, s25, v50
	v_lshlrev_b32_e32 v2, 6, v50
	v_ashrrev_i32_e32 v133, 31, v132
	s_and_saveexec_b64 s[0:1], vcc
	s_xor_b64 s[0:1], exec, s[0:1]
	v_lshlrev_b64 v[8:9], 13, v[132:133]
	v_ashrrev_i32_e32 v3, 31, v2
	v_lshl_add_u64 v[120:121], v[8:9], 0, v[2:3]
	s_andn2_saveexec_b64 s[0:1], s[0:1]
	v_lshlrev_b32_e32 v3, 8, v132
	v_add3_u32 v120, v2, v3, s26
	v_ashrrev_i32_e32 v121, 31, v120
	s_or_b64 exec, exec, s[0:1]
	global_load_dwordx2 v[48:49], v1, s[14:15] offset:48
	global_load_dwordx4 v[44:47], v1, s[14:15] offset:32
	global_load_dwordx4 v[8:11], v1, s[14:15] offset:16
	global_load_dwordx4 v[12:15], v1, s[14:15]
	v_and_b32_e32 v124, 63, v0
	v_and_b32_e32 v122, 15, v34
	v_mov_b32_e32 v123, v1
	v_lshlrev_b32_e32 v0, 5, v124
	v_lshl_add_u64 v[2:3], v[120:121], 0, v[122:123]
	v_lshl_add_u64 v[16:17], s[60:61], 0, v[0:1]
	v_and_b32_e32 v0, 48, v34
	v_and_b32_e32 v131, 63, v34
	v_lshl_add_u64 v[18:19], v[16:17], 0, v[0:1]
	v_mov_b32_e32 v16, 0
	v_lshlrev_b64 v[2:3], 13, v[2:3]
	v_cmp_lt_u32_e64 s[2:3], 31, v131
	v_cmp_gt_u32_e64 s[0:1], 32, v131
	v_lshl_add_u64 v[32:33], v[18:19], 0, v[2:3]
	v_mov_b32_e32 v17, v16
	v_mov_b32_e32 v18, v16
	v_mov_b32_e32 v19, v16
	s_and_saveexec_b64 s[10:11], s[0:1]
	s_cbranch_execz .LBB0_788
	global_load_dwordx4 v[16:19], v[32:33], off
